# stacked: attention rewrite with inline SGPR-base K/V staging + GEMM read rebalance + SGPR-base LDS-DMA + down-GEMM loop reads hoisted above address scalar code + write-through stores for MLP-up output
# speedup vs baseline: 1.0052x; 1.0052x over previous
; #define PG8_STAGE(bufoff, gbase, voff) do { _Pragma("unroll") for (int _i = 0; _i < 2; ++_i) \
;         __builtin_amdgcn_global_load_lds((const unsigned*)((const char*)(gbase) + (voff)[_i]), (LAS unsigned*)(lds + (bufoff) + ldsw + _i * 8192), 16, 0, 0); } while (0)
; #define PG8_LDA(dst, b, h) do { _Pragma("unroll") for (int m = 0; m < 4; ++m) _Pragma("unroll") for (int k = 0; k < 2; ++k) dst[m][k] = *(const LAS bf16x8*)(lds + PG8_SA(b, h) + aoff + m * 2048 + k * 1024); } while (0)
; #define PG8_LDB(dst, b, h) do { _Pragma("unroll") for (int n = 0; n < 2; ++n) _Pragma("unroll") for (int k = 0; k < 2; ++k) dst[n][k] = *(const LAS bf16x8*)(lds + PG8_SB(b, h) + boff + n * 2048 + k * 1024); } while (0)
; #define PG8_MMA(ai, bj, At, Bt) do { __builtin_amdgcn_s_setprio(1); _Pragma("unroll") for (int m = 0; m < 4; ++m) _Pragma("unroll") for (int n = 0; n < 2; ++n) _Pragma("unroll") for (int k = 0; k < 2; ++k) \
;         acc[ai][bj][m][n] = __builtin_amdgcn_mfma_f32_16x16x32_bf16(Bt[n][k], At[m][k], acc[ai][bj][m][n], 0, 0, 0); __builtin_amdgcn_s_setprio(0); } while (0)
; #define PG8_WAIT_V(n) asm volatile("s_waitcnt vmcnt(" #n ")" ::: "memory")
; template <class Epi>
; __device__ __forceinline__ void gemm_phase(LAS unsigned char* lds, const Gemm g, const StaticOrder& S, const Epi& E, int wv) {
;     ...
;             const bool last = (t == nt - 2);
;             const char* a1 = cA + (ptrdiff_t)(t + 1) * kstep;
;             const char* a2 = last ? nA : cA + (ptrdiff_t)(t + 2) * kstep; const char* b2 = last ? nB : cB + (ptrdiff_t)(t + 2) * kstep;
;             const char* a3 = a2 + kstep; const char* b3 = b2 + kstep;
;             PG8_LDB(B0, 0, 0); PG8_SCHED; PG8_LDA(At, 0, 0); PG8_STAGE(PG8_SA(1, 1), a1 + hstepA, voffA);
;             PG8_WAIT_L(8); PG8_BAR; PG8_WAIT_L(0); PG8_MMA(0, 0, At, B0); PG8_BAR; PG8_SCHED;
;             PG8_LDB(B1, 0, 1); PG8_STAGE(PG8_SB(0, 0), b2, voffB);
;             PG8_BAR; PG8_WAIT_L(0); PG8_MMA(0, 1, At, B1); PG8_BAR;
;             PG8_LDA(At, 0, 1); PG8_STAGE(PG8_SA(0, 0), a2, voffA);
;             PG8_BAR; PG8_WAIT_L(0); PG8_MMA(1, 0, At, B0); PG8_BAR; PG8_SCHED;
;             PG8_STAGE(PG8_SB(0, 1), b2 + hstepB, voffB);
;             PG8_WAIT_V(6); PG8_BAR; PG8_MMA(1, 1, At, B1); PG8_BAR;
;             PG8_LDB(B0, 1, 0); PG8_SCHED; PG8_LDA(At, 1, 0); PG8_STAGE(PG8_SA(0, 1), a2 + hstepA, voffA);
.LBB0_605:
	s_or_b32 s50, s35, 1
	s_lshl_b64 s[38:39], s[50:51], 7
	s_sub_u32 s38, 0, s38
	s_subb_u32 s39, 0, s39
	s_add_u32 s38, s33, s38
	s_addc_u32 s39, s34, s39
	s_add_i32 m0, s8, 0xc000
	global_load_lds_dwordx4 v144, s[38:39]
	s_add_i32 m0, s8, 0xe000
	s_nop 0
	global_load_lds_dwordx4 v148, s[38:39]
	s_waitcnt lgkmcnt(8)
	s_barrier
	s_waitcnt lgkmcnt(0)
	s_setprio 1
	s_waitcnt lgkmcnt(0)
	v_mfma_f32_16x16x32_bf16 v[124:127], v[128:131], v[156:159], v[124:127]
	v_mfma_f32_16x16x32_bf16 v[120:123], v[136:139], v[156:159], v[120:123]
	v_mfma_f32_16x16x32_bf16 v[108:111], v[128:131], v[164:167], v[108:111]
	v_mfma_f32_16x16x32_bf16 v[104:107], v[136:139], v[164:167], v[104:107]
	v_mfma_f32_16x16x32_bf16 v[92:95], v[128:131], v[176:179], v[92:95]
	v_mfma_f32_16x16x32_bf16 v[88:91], v[136:139], v[176:179], v[88:91]
	v_mfma_f32_16x16x32_bf16 v[76:79], v[128:131], v[184:187], v[76:79]
	v_mfma_f32_16x16x32_bf16 v[72:75], v[136:139], v[184:187], v[72:75]
	v_mfma_f32_16x16x32_bf16 v[124:127], v[132:135], v[160:163], v[124:127]
	v_mfma_f32_16x16x32_bf16 v[120:123], v[140:143], v[160:163], v[120:123]
	v_mfma_f32_16x16x32_bf16 v[108:111], v[132:135], v[168:171], v[108:111]
	v_mfma_f32_16x16x32_bf16 v[104:107], v[140:143], v[168:171], v[104:107]
	v_mfma_f32_16x16x32_bf16 v[92:95], v[132:135], v[180:183], v[92:95]
	v_mfma_f32_16x16x32_bf16 v[88:91], v[140:143], v[180:183], v[88:91]
	v_mfma_f32_16x16x32_bf16 v[76:79], v[132:135], v[188:191], v[76:79]
	v_mfma_f32_16x16x32_bf16 v[72:75], v[140:143], v[188:191], v[72:75]
	s_setprio 0
	s_barrier
	s_add_i32 s38, s22, s7
	v_add_u32_e32 v204, s23, v173
	s_add_u32 s98, s82, s58
	s_addc_u32 s99, s83, s59
	s_mov_b32 m0, s38
	ds_read_b128 v[192:195], v204
	ds_read_b128 v[196:199], v204 offset:1024
	ds_read_b128 v[200:203], v204 offset:2048
	ds_read_b128 v[204:207], v204 offset:3072
	global_load_lds_dwordx4 v146, s[82:83]
	s_add_i32 m0, s38, 0x2000
	s_nop 0
	global_load_lds_dwordx4 v150, s[82:83]
	s_barrier
	s_waitcnt lgkmcnt(0)
	s_setprio 1
	s_waitcnt lgkmcnt(0)
	v_mfma_f32_16x16x32_bf16 v[116:119], v[192:195], v[156:159], v[116:119]
	v_mfma_f32_16x16x32_bf16 v[112:115], v[200:203], v[156:159], v[112:115]
	v_mfma_f32_16x16x32_bf16 v[100:103], v[192:195], v[164:167], v[100:103]
	v_mfma_f32_16x16x32_bf16 v[96:99], v[200:203], v[164:167], v[96:99]
	v_mfma_f32_16x16x32_bf16 v[84:87], v[192:195], v[176:179], v[84:87]
	v_mfma_f32_16x16x32_bf16 v[80:83], v[200:203], v[176:179], v[80:83]
	v_mfma_f32_16x16x32_bf16 v[68:71], v[192:195], v[184:187], v[68:71]
	v_mfma_f32_16x16x32_bf16 v[64:67], v[200:203], v[184:187], v[64:67]
	v_mfma_f32_16x16x32_bf16 v[116:119], v[196:199], v[160:163], v[116:119]
	v_mfma_f32_16x16x32_bf16 v[112:115], v[204:207], v[160:163], v[112:115]
	v_mfma_f32_16x16x32_bf16 v[100:103], v[196:199], v[168:171], v[100:103]
	v_mfma_f32_16x16x32_bf16 v[96:99], v[204:207], v[168:171], v[96:99]
	v_mfma_f32_16x16x32_bf16 v[84:87], v[196:199], v[180:183], v[84:87]
	v_mfma_f32_16x16x32_bf16 v[80:83], v[204:207], v[180:183], v[80:83]
	v_mfma_f32_16x16x32_bf16 v[68:71], v[196:199], v[188:191], v[68:71]
	v_mfma_f32_16x16x32_bf16 v[64:67], v[204:207], v[188:191], v[64:67]
	s_setprio 0
	s_mov_b32 m0, s8
	s_add_u32 s100, s84, s58
	s_addc_u32 s101, s85, s59
	s_barrier
	ds_read_b128 v[156:159], v175 offset:16384
	ds_read_b128 v[160:163], v175 offset:17408
	ds_read_b128 v[164:167], v175 offset:18432
	ds_read_b128 v[168:171], v175 offset:19456
	ds_read_b128 v[176:179], v175 offset:20480
	ds_read_b128 v[180:183], v175 offset:21504
	ds_read_b128 v[184:187], v175 offset:22528
	ds_read_b128 v[188:191], v175 offset:23552
	global_load_lds_dwordx4 v144, s[84:85]
	s_mov_b32 m0, s9
	s_nop 0
	global_load_lds_dwordx4 v148, s[84:85]
	s_waitcnt vmcnt(10)
	s_barrier
	s_waitcnt lgkmcnt(0)
	s_setprio 1
	s_waitcnt lgkmcnt(0)
	v_mfma_f32_16x16x32_bf16 v[60:63], v[128:131], v[156:159], v[60:63]
	v_mfma_f32_16x16x32_bf16 v[56:59], v[136:139], v[156:159], v[56:59]
	v_mfma_f32_16x16x32_bf16 v[44:47], v[128:131], v[164:167], v[44:47]
	v_mfma_f32_16x16x32_bf16 v[40:43], v[136:139], v[164:167], v[40:43]
	v_mfma_f32_16x16x32_bf16 v[28:31], v[128:131], v[176:179], v[28:31]
	v_mfma_f32_16x16x32_bf16 v[24:27], v[136:139], v[176:179], v[24:27]
	v_mfma_f32_16x16x32_bf16 v[12:15], v[128:131], v[184:187], v[12:15]
	v_mfma_f32_16x16x32_bf16 v[8:11], v[136:139], v[184:187], v[8:11]
	v_mfma_f32_16x16x32_bf16 v[60:63], v[132:135], v[160:163], v[60:63]
	v_mfma_f32_16x16x32_bf16 v[56:59], v[140:143], v[160:163], v[56:59]
	v_mfma_f32_16x16x32_bf16 v[44:47], v[132:135], v[168:171], v[44:47]
	v_mfma_f32_16x16x32_bf16 v[40:43], v[140:143], v[168:171], v[40:43]
	v_mfma_f32_16x16x32_bf16 v[28:31], v[132:135], v[180:183], v[28:31]
	v_mfma_f32_16x16x32_bf16 v[24:27], v[140:143], v[180:183], v[24:27]
	v_mfma_f32_16x16x32_bf16 v[12:15], v[132:135], v[188:191], v[12:15]
	v_mfma_f32_16x16x32_bf16 v[8:11], v[140:143], v[188:191], v[8:11]
	s_setprio 0
	s_barrier
	s_add_u32 s38, s82, 0x200000
	s_addc_u32 s39, s83, 0
	s_add_i32 s40, s23, s7
	s_mov_b32 m0, s40
	s_nop 0
	global_load_lds_dwordx4 v146, s[38:39]
	s_add_i32 m0, s40, 0x2000
	s_nop 0
	global_load_lds_dwordx4 v150, s[38:39]
	s_add_i32 s40, 0, 0x18000
	v_add_u32_e32 v140, s40, v173
	ds_read_b128 v[128:131], v140
	ds_read_b128 v[132:135], v140 offset:1024
	ds_read_b128 v[136:139], v140 offset:2048
	ds_read_b128 v[140:143], v140 offset:3072
	s_waitcnt vmcnt(6)
	s_barrier
; #define PG8_STAGE(bufoff, gbase, voff) do { _Pragma("unroll") for (int _i = 0; _i < 2; ++_i) \
;         __builtin_amdgcn_global_load_lds((const unsigned*)((const char*)(gbase) + (voff)[_i]), (LAS unsigned*)(lds + (bufoff) + ldsw + _i * 8192), 16, 0, 0); } while (0)
; #define PG8_LDA(dst, b, h) do { _Pragma("unroll") for (int m = 0; m < 4; ++m) _Pragma("unroll") for (int k = 0; k < 2; ++k) dst[m][k] = *(const LAS bf16x8*)(lds + PG8_SA(b, h) + aoff + m * 2048 + k * 1024); } while (0)
; #define PG8_LDB(dst, b, h) do { _Pragma("unroll") for (int n = 0; n < 2; ++n) _Pragma("unroll") for (int k = 0; k < 2; ++k) dst[n][k] = *(const LAS bf16x8*)(lds + PG8_SB(b, h) + boff + n * 2048 + k * 1024); } while (0)
; #define PG8_MMA(ai, bj, At, Bt) do { __builtin_amdgcn_s_setprio(1); _Pragma("unroll") for (int m = 0; m < 4; ++m) _Pragma("unroll") for (int n = 0; n < 2; ++n) _Pragma("unroll") for (int k = 0; k < 2; ++k) \
;         acc[ai][bj][m][n] = __builtin_amdgcn_mfma_f32_16x16x32_bf16(Bt[n][k], At[m][k], acc[ai][bj][m][n], 0, 0, 0); __builtin_amdgcn_s_setprio(0); } while (0)
; #define PG8_WAIT_V(n) asm volatile("s_waitcnt vmcnt(" #n ")" ::: "memory")
; #define PG8_WAIT_L(n) asm volatile("s_waitcnt lgkmcnt(" #n ")" ::: "memory")
; #define PG8_BAR __builtin_amdgcn_s_barrier()
; #define PG8_SCHED __builtin_amdgcn_sched_barrier(0)
; template <class Epi>
; __device__ __forceinline__ void gemm_phase(LAS unsigned char* lds, const Gemm g, const StaticOrder& S, const Epi& E, int wv) {
;     ...
;             PG8_WAIT_V(6); PG8_BAR; PG8_MMA(1, 1, At, B1); PG8_BAR;
;             PG8_LDB(B0, 1, 0); PG8_SCHED; PG8_LDA(At, 1, 0); PG8_STAGE(PG8_SA(0, 1), a2 + hstepA, voffA);
;             PG8_WAIT_L(8); PG8_BAR; PG8_WAIT_L(0); PG8_MMA(0, 0, At, B0); PG8_BAR; PG8_SCHED;
;             PG8_LDB(B1, 1, 1); PG8_STAGE(PG8_SB(1, 0), b3, voffB);
;             PG8_BAR; PG8_WAIT_L(0); PG8_MMA(0, 1, At, B1); PG8_BAR;
;             PG8_LDA(At, 1, 1); PG8_STAGE(PG8_SA(1, 0), a3, voffA);
	s_setprio 1
	v_mfma_f32_16x16x32_bf16 v[52:55], v[192:195], v[156:159], v[52:55]
	v_mfma_f32_16x16x32_bf16 v[48:51], v[200:203], v[156:159], v[48:51]
	v_mfma_f32_16x16x32_bf16 v[36:39], v[192:195], v[164:167], v[36:39]
	v_mfma_f32_16x16x32_bf16 v[32:35], v[200:203], v[164:167], v[32:35]
	v_mfma_f32_16x16x32_bf16 v[20:23], v[192:195], v[176:179], v[20:23]
	v_mfma_f32_16x16x32_bf16 v[16:19], v[200:203], v[176:179], v[16:19]
	v_mfma_f32_16x16x32_bf16 v[4:7], v[192:195], v[184:187], v[4:7]
	v_mfma_f32_16x16x32_bf16 v[0:3], v[200:203], v[184:187], v[0:3]
	v_mfma_f32_16x16x32_bf16 v[52:55], v[196:199], v[160:163], v[52:55]
	v_mfma_f32_16x16x32_bf16 v[48:51], v[204:207], v[160:163], v[48:51]
	v_mfma_f32_16x16x32_bf16 v[36:39], v[196:199], v[168:171], v[36:39]
	v_mfma_f32_16x16x32_bf16 v[32:35], v[204:207], v[168:171], v[32:35]
	v_mfma_f32_16x16x32_bf16 v[20:23], v[196:199], v[180:183], v[20:23]
	v_mfma_f32_16x16x32_bf16 v[16:19], v[204:207], v[180:183], v[16:19]
	v_mfma_f32_16x16x32_bf16 v[4:7], v[196:199], v[188:191], v[4:7]
	v_mfma_f32_16x16x32_bf16 v[0:3], v[204:207], v[188:191], v[0:3]
	s_setprio 0
	s_waitcnt lgkmcnt(0)
	s_barrier
	s_add_u32 s38, s84, 0x200000
	s_addc_u32 s39, s85, 0
	s_mov_b32 m0, s10
	ds_read_b128 v[156:159], v175 offset:32768
	ds_read_b128 v[160:163], v175 offset:33792
	ds_read_b128 v[164:167], v175 offset:34816
	ds_read_b128 v[168:171], v175 offset:35840
	ds_read_b128 v[176:179], v175 offset:36864
	ds_read_b128 v[180:183], v175 offset:37888
	ds_read_b128 v[184:187], v175 offset:38912
	ds_read_b128 v[188:191], v175 offset:39936
	global_load_lds_dwordx4 v144, s[38:39]
	s_mov_b32 m0, s11
	s_nop 0
	global_load_lds_dwordx4 v148, s[38:39]
	s_waitcnt lgkmcnt(8)
	s_barrier
	s_waitcnt lgkmcnt(0)
	s_setprio 1
	s_waitcnt lgkmcnt(0)
	v_mfma_f32_16x16x32_bf16 v[124:127], v[128:131], v[156:159], v[124:127]
	v_mfma_f32_16x16x32_bf16 v[120:123], v[136:139], v[156:159], v[120:123]
	v_mfma_f32_16x16x32_bf16 v[108:111], v[128:131], v[164:167], v[108:111]
	v_mfma_f32_16x16x32_bf16 v[104:107], v[136:139], v[164:167], v[104:107]
	v_mfma_f32_16x16x32_bf16 v[92:95], v[128:131], v[176:179], v[92:95]
	v_mfma_f32_16x16x32_bf16 v[88:91], v[136:139], v[176:179], v[88:91]
	v_mfma_f32_16x16x32_bf16 v[76:79], v[128:131], v[184:187], v[76:79]
	v_mfma_f32_16x16x32_bf16 v[72:75], v[136:139], v[184:187], v[72:75]
	v_mfma_f32_16x16x32_bf16 v[124:127], v[132:135], v[160:163], v[124:127]
	v_mfma_f32_16x16x32_bf16 v[120:123], v[140:143], v[160:163], v[120:123]
	v_mfma_f32_16x16x32_bf16 v[108:111], v[132:135], v[168:171], v[108:111]
	v_mfma_f32_16x16x32_bf16 v[104:107], v[140:143], v[168:171], v[104:107]
	v_mfma_f32_16x16x32_bf16 v[92:95], v[132:135], v[180:183], v[92:95]
	v_mfma_f32_16x16x32_bf16 v[88:91], v[140:143], v[180:183], v[88:91]
	v_mfma_f32_16x16x32_bf16 v[76:79], v[132:135], v[188:191], v[76:79]
	v_mfma_f32_16x16x32_bf16 v[72:75], v[140:143], v[188:191], v[72:75]
	s_setprio 0
	s_barrier
	s_add_i32 s41, 0, 0x1c000
	s_add_i32 s38, s40, s7
	v_add_u32_e32 v204, s41, v173
	s_mov_b32 m0, s38
	ds_read_b128 v[192:195], v204
	ds_read_b128 v[196:199], v204 offset:1024
	ds_read_b128 v[200:203], v204 offset:2048
	ds_read_b128 v[204:207], v204 offset:3072
	global_load_lds_dwordx4 v146, s[98:99]
	s_add_i32 m0, s38, 0x2000
	s_nop 0
	global_load_lds_dwordx4 v150, s[98:99]
	s_barrier
	s_waitcnt lgkmcnt(0)
	s_setprio 1
	s_waitcnt lgkmcnt(0)
	v_mfma_f32_16x16x32_bf16 v[116:119], v[192:195], v[156:159], v[116:119]
	v_mfma_f32_16x16x32_bf16 v[112:115], v[200:203], v[156:159], v[112:115]
	v_mfma_f32_16x16x32_bf16 v[100:103], v[192:195], v[164:167], v[100:103]
	v_mfma_f32_16x16x32_bf16 v[96:99], v[200:203], v[164:167], v[96:99]
	v_mfma_f32_16x16x32_bf16 v[84:87], v[192:195], v[176:179], v[84:87]
	v_mfma_f32_16x16x32_bf16 v[80:83], v[200:203], v[176:179], v[80:83]
	v_mfma_f32_16x16x32_bf16 v[68:71], v[192:195], v[184:187], v[68:71]
	v_mfma_f32_16x16x32_bf16 v[64:67], v[200:203], v[184:187], v[64:67]
	v_mfma_f32_16x16x32_bf16 v[116:119], v[196:199], v[160:163], v[116:119]
	v_mfma_f32_16x16x32_bf16 v[112:115], v[204:207], v[160:163], v[112:115]
	v_mfma_f32_16x16x32_bf16 v[100:103], v[196:199], v[168:171], v[100:103]
	v_mfma_f32_16x16x32_bf16 v[96:99], v[204:207], v[168:171], v[96:99]
	v_mfma_f32_16x16x32_bf16 v[84:87], v[196:199], v[180:183], v[84:87]
	v_mfma_f32_16x16x32_bf16 v[80:83], v[204:207], v[180:183], v[80:83]
	v_mfma_f32_16x16x32_bf16 v[68:71], v[196:199], v[188:191], v[68:71]
	v_mfma_f32_16x16x32_bf16 v[64:67], v[204:207], v[188:191], v[64:67]
	s_setprio 0
	s_mov_b32 m0, s12
	s_barrier
; #define PG8_STAGE(bufoff, gbase, voff) do { _Pragma("unroll") for (int _i = 0; _i < 2; ++_i) \
;         __builtin_amdgcn_global_load_lds((const unsigned*)((const char*)(gbase) + (voff)[_i]), (LAS unsigned*)(lds + (bufoff) + ldsw + _i * 8192), 16, 0, 0); } while (0)
; #define PG8_LDA(dst, b, h) do { _Pragma("unroll") for (int m = 0; m < 4; ++m) _Pragma("unroll") for (int k = 0; k < 2; ++k) dst[m][k] = *(const LAS bf16x8*)(lds + PG8_SA(b, h) + aoff + m * 2048 + k * 1024); } while (0)
; #define PG8_LDB(dst, b, h) do { _Pragma("unroll") for (int n = 0; n < 2; ++n) _Pragma("unroll") for (int k = 0; k < 2; ++k) dst[n][k] = *(const LAS bf16x8*)(lds + PG8_SB(b, h) + boff + n * 2048 + k * 1024); } while (0)
; #define PG8_MMA(ai, bj, At, Bt) do { __builtin_amdgcn_s_setprio(1); _Pragma("unroll") for (int m = 0; m < 4; ++m) _Pragma("unroll") for (int n = 0; n < 2; ++n) _Pragma("unroll") for (int k = 0; k < 2; ++k) \
;         acc[ai][bj][m][n] = __builtin_amdgcn_mfma_f32_16x16x32_bf16(Bt[n][k], At[m][k], acc[ai][bj][m][n], 0, 0, 0); __builtin_amdgcn_s_setprio(0); } while (0)
; #define PG8_WAIT_V(n) asm volatile("s_waitcnt vmcnt(" #n ")" ::: "memory")
; #define PG8_WAIT_L(n) asm volatile("s_waitcnt lgkmcnt(" #n ")" ::: "memory")
; #define PG8_BAR __builtin_amdgcn_s_barrier()
; #define PG8_SCHED __builtin_amdgcn_sched_barrier(0)
; template <class Epi>
; __device__ __forceinline__ void gemm_phase(LAS unsigned char* lds, const Gemm g, const StaticOrder& S, const Epi& E, int wv) {
;     ...
;             const bool last = (t == nt - 2);
;             const char* a1 = cA + (ptrdiff_t)(t + 1) * kstep;
;             const char* a2 = last ? nA : cA + (ptrdiff_t)(t + 2) * kstep; const char* b2 = last ? nB : cB + (ptrdiff_t)(t + 2) * kstep;
;             const char* a3 = a2 + kstep; const char* b3 = b2 + kstep;
;             PG8_LDB(B0, 0, 0); PG8_SCHED; PG8_LDA(At, 0, 0); PG8_STAGE(PG8_SA(1, 1), a1 + hstepA, voffA);
;     ...
;             PG8_LDB(B1, 1, 1); PG8_STAGE(PG8_SB(1, 0), b3, voffB);
;             PG8_BAR; PG8_WAIT_L(0); PG8_MMA(0, 1, At, B1); PG8_BAR;
;             PG8_LDA(At, 1, 1); PG8_STAGE(PG8_SA(1, 0), a3, voffA);
;             PG8_BAR; PG8_WAIT_L(0); PG8_MMA(1, 0, At, B0); PG8_BAR; PG8_SCHED;
;             PG8_STAGE(PG8_SB(1, 1), b3 + hstepB, voffB);
;             PG8_WAIT_V(6); PG8_BAR; PG8_MMA(1, 1, At, B1); PG8_BAR;
	ds_read_b128 v[156:159], v175 offset:49152
	ds_read_b128 v[160:163], v175 offset:50176
	ds_read_b128 v[164:167], v175 offset:51200
	ds_read_b128 v[168:171], v175 offset:52224
	ds_read_b128 v[176:179], v175 offset:53248
	ds_read_b128 v[180:183], v175 offset:54272
	ds_read_b128 v[184:187], v175 offset:55296
	ds_read_b128 v[188:191], v175 offset:56320
	global_load_lds_dwordx4 v144, s[100:101]
	s_mov_b32 m0, s13
	s_nop 0
	global_load_lds_dwordx4 v148, s[100:101]
	s_waitcnt vmcnt(10)
	s_barrier
	s_waitcnt lgkmcnt(0)
	s_setprio 1
	s_waitcnt lgkmcnt(0)
	v_mfma_f32_16x16x32_bf16 v[60:63], v[128:131], v[156:159], v[60:63]
	v_mfma_f32_16x16x32_bf16 v[56:59], v[136:139], v[156:159], v[56:59]
	v_mfma_f32_16x16x32_bf16 v[44:47], v[128:131], v[164:167], v[44:47]
	v_mfma_f32_16x16x32_bf16 v[40:43], v[136:139], v[164:167], v[40:43]
	v_mfma_f32_16x16x32_bf16 v[28:31], v[128:131], v[176:179], v[28:31]
	v_mfma_f32_16x16x32_bf16 v[24:27], v[136:139], v[176:179], v[24:27]
	v_mfma_f32_16x16x32_bf16 v[12:15], v[128:131], v[184:187], v[12:15]
	v_mfma_f32_16x16x32_bf16 v[8:11], v[136:139], v[184:187], v[8:11]
	v_mfma_f32_16x16x32_bf16 v[60:63], v[132:135], v[160:163], v[60:63]
	v_mfma_f32_16x16x32_bf16 v[56:59], v[140:143], v[160:163], v[56:59]
	v_mfma_f32_16x16x32_bf16 v[44:47], v[132:135], v[168:171], v[44:47]
	v_mfma_f32_16x16x32_bf16 v[40:43], v[140:143], v[168:171], v[40:43]
	v_mfma_f32_16x16x32_bf16 v[28:31], v[132:135], v[180:183], v[28:31]
	v_mfma_f32_16x16x32_bf16 v[24:27], v[140:143], v[180:183], v[24:27]
	v_mfma_f32_16x16x32_bf16 v[12:15], v[132:135], v[188:191], v[12:15]
	v_mfma_f32_16x16x32_bf16 v[8:11], v[140:143], v[188:191], v[8:11]
	s_setprio 0
	s_barrier
	s_add_u32 s38, s82, 0x1fff80
	s_addc_u32 s39, s83, 0
	s_add_i32 s40, s41, s7
	s_mov_b32 m0, s40
	s_nop 0
	global_load_lds_dwordx4 v146, s[38:39]
	s_add_i32 m0, s40, 0x2000
	s_nop 0
	global_load_lds_dwordx4 v150, s[38:39]
	v_add_u32_e32 v140, s22, v173
	ds_read_b128 v[128:131], v140
	ds_read_b128 v[132:135], v140 offset:1024
	ds_read_b128 v[136:139], v140 offset:2048
	ds_read_b128 v[140:143], v140 offset:3072
	s_waitcnt vmcnt(6)
	s_barrier
	s_setprio 1
	v_mfma_f32_16x16x32_bf16 v[52:55], v[192:195], v[156:159], v[52:55]
	v_mfma_f32_16x16x32_bf16 v[48:51], v[200:203], v[156:159], v[48:51]
	v_mfma_f32_16x16x32_bf16 v[36:39], v[192:195], v[164:167], v[36:39]
	v_mfma_f32_16x16x32_bf16 v[32:35], v[200:203], v[164:167], v[32:35]
	v_mfma_f32_16x16x32_bf16 v[20:23], v[192:195], v[176:179], v[20:23]
	v_mfma_f32_16x16x32_bf16 v[16:19], v[200:203], v[176:179], v[16:19]
	v_mfma_f32_16x16x32_bf16 v[4:7], v[192:195], v[184:187], v[4:7]
	v_mfma_f32_16x16x32_bf16 v[0:3], v[200:203], v[184:187], v[0:3]
	v_mfma_f32_16x16x32_bf16 v[52:55], v[196:199], v[160:163], v[52:55]
	v_mfma_f32_16x16x32_bf16 v[48:51], v[204:207], v[160:163], v[48:51]
	v_mfma_f32_16x16x32_bf16 v[36:39], v[196:199], v[168:171], v[36:39]
	v_mfma_f32_16x16x32_bf16 v[32:35], v[204:207], v[168:171], v[32:35]
	v_mfma_f32_16x16x32_bf16 v[20:23], v[196:199], v[180:183], v[20:23]
	v_mfma_f32_16x16x32_bf16 v[16:19], v[204:207], v[180:183], v[16:19]
	v_mfma_f32_16x16x32_bf16 v[4:7], v[196:199], v[188:191], v[4:7]
	v_mfma_f32_16x16x32_bf16 v[0:3], v[204:207], v[188:191], v[0:3]
	s_setprio 0
	s_waitcnt lgkmcnt(0)
	s_cmpk_gt_u32 s35, 0x7d
	s_mov_b32 s35, s80
	s_barrier
	s_cbranch_scc1 .LBB0_610
.LBB0_606:
	ds_read_b128 v[156:159], v175
	ds_read_b128 v[160:163], v175 offset:1024
	ds_read_b128 v[164:167], v175 offset:2048
	ds_read_b128 v[168:171], v175 offset:3072
	ds_read_b128 v[176:179], v175 offset:4096
	ds_read_b128 v[180:183], v175 offset:5120
	ds_read_b128 v[184:187], v175 offset:6144
	ds_read_b128 v[188:191], v175 offset:7168
	s_cmpk_lg_i32 s35, 0x7e
	s_movk_i32 s80, 0x80
	s_cselect_b64 s[82:83], -1, 0
	s_cmpk_eq_i32 s35, 0x7e
	s_mov_b64 s[84:85], s[76:77]
	s_cbranch_scc1 .LBB0_608
	s_add_i32 s50, s35, 2
	s_lshl_b64 s[38:39], s[50:51], 7
	s_sub_u32 s38, 0, s38
	s_subb_u32 s39, 0, s39
	s_add_u32 s84, s74, s38
	s_addc_u32 s85, s75, s39
	s_mov_b32 s80, s50

; #define PG8_STAGE(bufoff, gbase, voff) do { _Pragma("unroll") for (int _i = 0; _i < 2; ++_i) \
;         __builtin_amdgcn_global_load_lds((const unsigned*)((const char*)(gbase) + (voff)[_i]), (LAS unsigned*)(lds + (bufoff) + ldsw + _i * 8192), 16, 0, 0); } while (0)
; #define PG8_LDA(dst, b, h) do { _Pragma("unroll") for (int m = 0; m < 4; ++m) _Pragma("unroll") for (int k = 0; k < 2; ++k) dst[m][k] = *(const LAS bf16x8*)(lds + PG8_SA(b, h) + aoff + m * 2048 + k * 1024); } while (0)
; #define PG8_LDB(dst, b, h) do { _Pragma("unroll") for (int n = 0; n < 2; ++n) _Pragma("unroll") for (int k = 0; k < 2; ++k) dst[n][k] = *(const LAS bf16x8*)(lds + PG8_SB(b, h) + boff + n * 2048 + k * 1024); } while (0)
; #define PG8_MMA(ai, bj, At, Bt) do { __builtin_amdgcn_s_setprio(1); _Pragma("unroll") for (int m = 0; m < 4; ++m) _Pragma("unroll") for (int n = 0; n < 2; ++n) _Pragma("unroll") for (int k = 0; k < 2; ++k) \
;         acc[ai][bj][m][n] = __builtin_amdgcn_mfma_f32_16x16x32_bf16(Bt[n][k], At[m][k], acc[ai][bj][m][n], 0, 0, 0); __builtin_amdgcn_s_setprio(0); } while (0)
; #define PG8_WAIT_V(n) asm volatile("s_waitcnt vmcnt(" #n ")" ::: "memory")
; template <class Epi>
; __device__ __forceinline__ void gemm_phase(LAS unsigned char* lds, const Gemm g, const StaticOrder& S, const Epi& E, int wv) {
;     ...
;             const bool last = (t == nt - 2);
;             const char* a1 = cA + (ptrdiff_t)(t + 1) * kstep;
;             const char* a2 = last ? nA : cA + (ptrdiff_t)(t + 2) * kstep; const char* b2 = last ? nB : cB + (ptrdiff_t)(t + 2) * kstep;
;             const char* a3 = a2 + kstep; const char* b3 = b2 + kstep;
;             PG8_LDB(B0, 0, 0); PG8_SCHED; PG8_LDA(At, 0, 0); PG8_STAGE(PG8_SA(1, 1), a1 + hstepA, voffA);
;             PG8_WAIT_L(8); PG8_BAR; PG8_WAIT_L(0); PG8_MMA(0, 0, At, B0); PG8_BAR; PG8_SCHED;
;             PG8_LDB(B1, 0, 1); PG8_STAGE(PG8_SB(0, 0), b2, voffB);
;             PG8_BAR; PG8_WAIT_L(0); PG8_MMA(0, 1, At, B1); PG8_BAR;
;             PG8_LDA(At, 0, 1); PG8_STAGE(PG8_SA(0, 0), a2, voffA);
;             PG8_BAR; PG8_WAIT_L(0); PG8_MMA(1, 0, At, B0); PG8_BAR; PG8_SCHED;
;             PG8_STAGE(PG8_SB(0, 1), b2 + hstepB, voffB);
;             PG8_WAIT_V(6); PG8_BAR; PG8_MMA(1, 1, At, B1); PG8_BAR;
;             PG8_LDB(B0, 1, 0); PG8_SCHED; PG8_LDA(At, 1, 0); PG8_STAGE(PG8_SA(0, 1), a2 + hstepA, voffA);
.LBB0_1743:
	s_or_b32 s10, s43, 1
	s_lshl_b64 s[68:69], s[10:11], 7
	s_sub_u32 s10, 0, s68
	s_subb_u32 s55, 0, s69
	s_add_u32 s68, s35, s10
	s_addc_u32 s69, s37, s55
	s_add_i32 m0, s24, 0xc000
	global_load_lds_dwordx4 v144, s[68:69]
	s_add_i32 m0, s24, 0xe000
	s_nop 0
	global_load_lds_dwordx4 v148, s[68:69]
	s_waitcnt lgkmcnt(8)
	s_barrier
	s_waitcnt lgkmcnt(0)
	s_setprio 1
	s_waitcnt lgkmcnt(0)
	v_mfma_f32_16x16x32_bf16 v[124:127], v[128:131], v[156:159], v[124:127]
	v_mfma_f32_16x16x32_bf16 v[120:123], v[136:139], v[156:159], v[120:123]
	v_mfma_f32_16x16x32_bf16 v[108:111], v[128:131], v[164:167], v[108:111]
	v_mfma_f32_16x16x32_bf16 v[104:107], v[136:139], v[164:167], v[104:107]
	v_mfma_f32_16x16x32_bf16 v[92:95], v[128:131], v[176:179], v[92:95]
	v_mfma_f32_16x16x32_bf16 v[88:91], v[136:139], v[176:179], v[88:91]
	v_mfma_f32_16x16x32_bf16 v[76:79], v[128:131], v[184:187], v[76:79]
	v_mfma_f32_16x16x32_bf16 v[72:75], v[136:139], v[184:187], v[72:75]
	v_mfma_f32_16x16x32_bf16 v[124:127], v[132:135], v[160:163], v[124:127]
	v_mfma_f32_16x16x32_bf16 v[120:123], v[140:143], v[160:163], v[120:123]
	v_mfma_f32_16x16x32_bf16 v[108:111], v[132:135], v[168:171], v[108:111]
	v_mfma_f32_16x16x32_bf16 v[104:107], v[140:143], v[168:171], v[104:107]
	v_mfma_f32_16x16x32_bf16 v[92:95], v[132:135], v[180:183], v[92:95]
	v_mfma_f32_16x16x32_bf16 v[88:91], v[140:143], v[180:183], v[88:91]
	v_mfma_f32_16x16x32_bf16 v[76:79], v[132:135], v[188:191], v[76:79]
	v_mfma_f32_16x16x32_bf16 v[72:75], v[140:143], v[188:191], v[72:75]
	s_setprio 0
	s_barrier
	s_add_i32 s10, s64, s23
	v_add_u32_e32 v204, s65, v173
	s_add_u32 s98, s56, s18
	s_addc_u32 s99, s57, s19
	s_mov_b32 m0, s10
	ds_read_b128 v[192:195], v204
	ds_read_b128 v[196:199], v204 offset:1024
	ds_read_b128 v[200:203], v204 offset:2048
	ds_read_b128 v[204:207], v204 offset:3072
	global_load_lds_dwordx4 v146, s[56:57]
	s_add_i32 m0, s10, 0x2000
	s_nop 0
	global_load_lds_dwordx4 v150, s[56:57]
	s_barrier
	s_waitcnt lgkmcnt(0)
	s_setprio 1
	s_waitcnt lgkmcnt(0)
	v_mfma_f32_16x16x32_bf16 v[116:119], v[192:195], v[156:159], v[116:119]
	v_mfma_f32_16x16x32_bf16 v[112:115], v[200:203], v[156:159], v[112:115]
	v_mfma_f32_16x16x32_bf16 v[100:103], v[192:195], v[164:167], v[100:103]
	v_mfma_f32_16x16x32_bf16 v[96:99], v[200:203], v[164:167], v[96:99]
	v_mfma_f32_16x16x32_bf16 v[84:87], v[192:195], v[176:179], v[84:87]
	v_mfma_f32_16x16x32_bf16 v[80:83], v[200:203], v[176:179], v[80:83]
	v_mfma_f32_16x16x32_bf16 v[68:71], v[192:195], v[184:187], v[68:71]
	v_mfma_f32_16x16x32_bf16 v[64:67], v[200:203], v[184:187], v[64:67]
	v_mfma_f32_16x16x32_bf16 v[116:119], v[196:199], v[160:163], v[116:119]
	v_mfma_f32_16x16x32_bf16 v[112:115], v[204:207], v[160:163], v[112:115]
	v_mfma_f32_16x16x32_bf16 v[100:103], v[196:199], v[168:171], v[100:103]
	v_mfma_f32_16x16x32_bf16 v[96:99], v[204:207], v[168:171], v[96:99]
	v_mfma_f32_16x16x32_bf16 v[84:87], v[196:199], v[180:183], v[84:87]
	v_mfma_f32_16x16x32_bf16 v[80:83], v[204:207], v[180:183], v[80:83]
	v_mfma_f32_16x16x32_bf16 v[68:71], v[196:199], v[188:191], v[68:71]
	v_mfma_f32_16x16x32_bf16 v[64:67], v[204:207], v[188:191], v[64:67]
	s_setprio 0
	s_mov_b32 m0, s24
	s_add_u32 s100, s58, s18
	s_addc_u32 s101, s59, s19
	s_barrier
	ds_read_b128 v[156:159], v175 offset:16384
	ds_read_b128 v[160:163], v175 offset:17408
	ds_read_b128 v[164:167], v175 offset:18432
	ds_read_b128 v[168:171], v175 offset:19456
	ds_read_b128 v[176:179], v175 offset:20480
	ds_read_b128 v[180:183], v175 offset:21504
	ds_read_b128 v[184:187], v175 offset:22528
	ds_read_b128 v[188:191], v175 offset:23552
	global_load_lds_dwordx4 v144, s[58:59]
	s_mov_b32 m0, s25
	s_nop 0
	global_load_lds_dwordx4 v148, s[58:59]
	s_waitcnt vmcnt(10)
	s_barrier
	s_waitcnt lgkmcnt(0)
	s_setprio 1
	s_waitcnt lgkmcnt(0)
	v_mfma_f32_16x16x32_bf16 v[60:63], v[128:131], v[156:159], v[60:63]
	v_mfma_f32_16x16x32_bf16 v[56:59], v[136:139], v[156:159], v[56:59]
	v_mfma_f32_16x16x32_bf16 v[44:47], v[128:131], v[164:167], v[44:47]
	v_mfma_f32_16x16x32_bf16 v[40:43], v[136:139], v[164:167], v[40:43]
	v_mfma_f32_16x16x32_bf16 v[28:31], v[128:131], v[176:179], v[28:31]
	v_mfma_f32_16x16x32_bf16 v[24:27], v[136:139], v[176:179], v[24:27]
	v_mfma_f32_16x16x32_bf16 v[12:15], v[128:131], v[184:187], v[12:15]
	v_mfma_f32_16x16x32_bf16 v[8:11], v[136:139], v[184:187], v[8:11]
	v_mfma_f32_16x16x32_bf16 v[60:63], v[132:135], v[160:163], v[60:63]
	v_mfma_f32_16x16x32_bf16 v[56:59], v[140:143], v[160:163], v[56:59]
	v_mfma_f32_16x16x32_bf16 v[44:47], v[132:135], v[168:171], v[44:47]
	v_mfma_f32_16x16x32_bf16 v[40:43], v[140:143], v[168:171], v[40:43]
	v_mfma_f32_16x16x32_bf16 v[28:31], v[132:135], v[180:183], v[28:31]
	v_mfma_f32_16x16x32_bf16 v[24:27], v[140:143], v[180:183], v[24:27]
	v_mfma_f32_16x16x32_bf16 v[12:15], v[132:135], v[188:191], v[12:15]
	v_mfma_f32_16x16x32_bf16 v[8:11], v[140:143], v[188:191], v[8:11]
	s_setprio 0
	s_barrier
	s_add_u32 s68, s56, 0x200000
	s_addc_u32 s69, s57, 0
	s_add_i32 s10, s65, s23
	s_mov_b32 m0, s10
	s_nop 0
	global_load_lds_dwordx4 v146, s[68:69]
	s_add_i32 m0, s10, 0x2000
	s_nop 0
	global_load_lds_dwordx4 v150, s[68:69]
	s_add_i32 s10, 0, 0x18000
	v_add_u32_e32 v140, s10, v173
	ds_read_b128 v[128:131], v140
	ds_read_b128 v[132:135], v140 offset:1024
	ds_read_b128 v[136:139], v140 offset:2048
	ds_read_b128 v[140:143], v140 offset:3072
	s_waitcnt vmcnt(6)
	s_barrier
; #define PG8_STAGE(bufoff, gbase, voff) do { _Pragma("unroll") for (int _i = 0; _i < 2; ++_i) \
;         __builtin_amdgcn_global_load_lds((const unsigned*)((const char*)(gbase) + (voff)[_i]), (LAS unsigned*)(lds + (bufoff) + ldsw + _i * 8192), 16, 0, 0); } while (0)
; #define PG8_LDA(dst, b, h) do { _Pragma("unroll") for (int m = 0; m < 4; ++m) _Pragma("unroll") for (int k = 0; k < 2; ++k) dst[m][k] = *(const LAS bf16x8*)(lds + PG8_SA(b, h) + aoff + m * 2048 + k * 1024); } while (0)
; #define PG8_LDB(dst, b, h) do { _Pragma("unroll") for (int n = 0; n < 2; ++n) _Pragma("unroll") for (int k = 0; k < 2; ++k) dst[n][k] = *(const LAS bf16x8*)(lds + PG8_SB(b, h) + boff + n * 2048 + k * 1024); } while (0)
; #define PG8_MMA(ai, bj, At, Bt) do { __builtin_amdgcn_s_setprio(1); _Pragma("unroll") for (int m = 0; m < 4; ++m) _Pragma("unroll") for (int n = 0; n < 2; ++n) _Pragma("unroll") for (int k = 0; k < 2; ++k) \
;         acc[ai][bj][m][n] = __builtin_amdgcn_mfma_f32_16x16x32_bf16(Bt[n][k], At[m][k], acc[ai][bj][m][n], 0, 0, 0); __builtin_amdgcn_s_setprio(0); } while (0)
; #define PG8_WAIT_V(n) asm volatile("s_waitcnt vmcnt(" #n ")" ::: "memory")
; #define PG8_WAIT_L(n) asm volatile("s_waitcnt lgkmcnt(" #n ")" ::: "memory")
; #define PG8_BAR __builtin_amdgcn_s_barrier()
; #define PG8_SCHED __builtin_amdgcn_sched_barrier(0)
; template <class Epi>
; __device__ __forceinline__ void gemm_phase(LAS unsigned char* lds, const Gemm g, const StaticOrder& S, const Epi& E, int wv) {
;     ...
;             PG8_WAIT_V(6); PG8_BAR; PG8_MMA(1, 1, At, B1); PG8_BAR;
;             PG8_LDB(B0, 1, 0); PG8_SCHED; PG8_LDA(At, 1, 0); PG8_STAGE(PG8_SA(0, 1), a2 + hstepA, voffA);
;             PG8_WAIT_L(8); PG8_BAR; PG8_WAIT_L(0); PG8_MMA(0, 0, At, B0); PG8_BAR; PG8_SCHED;
;             PG8_LDB(B1, 1, 1); PG8_STAGE(PG8_SB(1, 0), b3, voffB);
;             PG8_BAR; PG8_WAIT_L(0); PG8_MMA(0, 1, At, B1); PG8_BAR;
;             PG8_LDA(At, 1, 1); PG8_STAGE(PG8_SA(1, 0), a3, voffA);
	s_setprio 1
	v_mfma_f32_16x16x32_bf16 v[52:55], v[192:195], v[156:159], v[52:55]
	v_mfma_f32_16x16x32_bf16 v[48:51], v[200:203], v[156:159], v[48:51]
	v_mfma_f32_16x16x32_bf16 v[36:39], v[192:195], v[164:167], v[36:39]
	v_mfma_f32_16x16x32_bf16 v[32:35], v[200:203], v[164:167], v[32:35]
	v_mfma_f32_16x16x32_bf16 v[20:23], v[192:195], v[176:179], v[20:23]
	v_mfma_f32_16x16x32_bf16 v[16:19], v[200:203], v[176:179], v[16:19]
	v_mfma_f32_16x16x32_bf16 v[4:7], v[192:195], v[184:187], v[4:7]
	v_mfma_f32_16x16x32_bf16 v[0:3], v[200:203], v[184:187], v[0:3]
	v_mfma_f32_16x16x32_bf16 v[52:55], v[196:199], v[160:163], v[52:55]
	v_mfma_f32_16x16x32_bf16 v[48:51], v[204:207], v[160:163], v[48:51]
	v_mfma_f32_16x16x32_bf16 v[36:39], v[196:199], v[168:171], v[36:39]
	v_mfma_f32_16x16x32_bf16 v[32:35], v[204:207], v[168:171], v[32:35]
	v_mfma_f32_16x16x32_bf16 v[20:23], v[196:199], v[180:183], v[20:23]
	v_mfma_f32_16x16x32_bf16 v[16:19], v[204:207], v[180:183], v[16:19]
	v_mfma_f32_16x16x32_bf16 v[4:7], v[196:199], v[188:191], v[4:7]
	v_mfma_f32_16x16x32_bf16 v[0:3], v[204:207], v[188:191], v[0:3]
	s_setprio 0
	s_waitcnt lgkmcnt(0)
	s_barrier
	s_add_u32 s58, s58, 0x200000
	s_addc_u32 s59, s59, 0
	s_mov_b32 m0, s33
	ds_read_b128 v[156:159], v175 offset:32768
	ds_read_b128 v[160:163], v175 offset:33792
	ds_read_b128 v[164:167], v175 offset:34816
	ds_read_b128 v[168:171], v175 offset:35840
	ds_read_b128 v[176:179], v175 offset:36864
	ds_read_b128 v[180:183], v175 offset:37888
	ds_read_b128 v[184:187], v175 offset:38912
	ds_read_b128 v[188:191], v175 offset:39936
	global_load_lds_dwordx4 v144, s[58:59]
	s_mov_b32 m0, s45
	s_nop 0
	global_load_lds_dwordx4 v148, s[58:59]
	s_waitcnt lgkmcnt(8)
	s_barrier
	s_waitcnt lgkmcnt(0)
	s_setprio 1
	s_waitcnt lgkmcnt(0)
	v_mfma_f32_16x16x32_bf16 v[124:127], v[128:131], v[156:159], v[124:127]
	v_mfma_f32_16x16x32_bf16 v[120:123], v[136:139], v[156:159], v[120:123]
	v_mfma_f32_16x16x32_bf16 v[108:111], v[128:131], v[164:167], v[108:111]
	v_mfma_f32_16x16x32_bf16 v[104:107], v[136:139], v[164:167], v[104:107]
	v_mfma_f32_16x16x32_bf16 v[92:95], v[128:131], v[176:179], v[92:95]
	v_mfma_f32_16x16x32_bf16 v[88:91], v[136:139], v[176:179], v[88:91]
	v_mfma_f32_16x16x32_bf16 v[76:79], v[128:131], v[184:187], v[76:79]
	v_mfma_f32_16x16x32_bf16 v[72:75], v[136:139], v[184:187], v[72:75]
	v_mfma_f32_16x16x32_bf16 v[124:127], v[132:135], v[160:163], v[124:127]
	v_mfma_f32_16x16x32_bf16 v[120:123], v[140:143], v[160:163], v[120:123]
	v_mfma_f32_16x16x32_bf16 v[108:111], v[132:135], v[168:171], v[108:111]
	v_mfma_f32_16x16x32_bf16 v[104:107], v[140:143], v[168:171], v[104:107]
	v_mfma_f32_16x16x32_bf16 v[92:95], v[132:135], v[180:183], v[92:95]
	v_mfma_f32_16x16x32_bf16 v[88:91], v[140:143], v[180:183], v[88:91]
	v_mfma_f32_16x16x32_bf16 v[76:79], v[132:135], v[188:191], v[76:79]
	v_mfma_f32_16x16x32_bf16 v[72:75], v[140:143], v[188:191], v[72:75]
	s_setprio 0
	s_barrier
	s_add_i32 s55, 0, 0x1c000
	s_add_i32 s10, s10, s23
	v_add_u32_e32 v204, s55, v173
	s_mov_b32 m0, s10
	ds_read_b128 v[192:195], v204
	ds_read_b128 v[196:199], v204 offset:1024
	ds_read_b128 v[200:203], v204 offset:2048
	ds_read_b128 v[204:207], v204 offset:3072
	global_load_lds_dwordx4 v146, s[98:99]
	s_add_i32 m0, s10, 0x2000
	s_nop 0
	global_load_lds_dwordx4 v150, s[98:99]
	s_barrier
	s_waitcnt lgkmcnt(0)
	s_setprio 1
	s_waitcnt lgkmcnt(0)
	v_mfma_f32_16x16x32_bf16 v[116:119], v[192:195], v[156:159], v[116:119]
	v_mfma_f32_16x16x32_bf16 v[112:115], v[200:203], v[156:159], v[112:115]
	v_mfma_f32_16x16x32_bf16 v[100:103], v[192:195], v[164:167], v[100:103]
	v_mfma_f32_16x16x32_bf16 v[96:99], v[200:203], v[164:167], v[96:99]
	v_mfma_f32_16x16x32_bf16 v[84:87], v[192:195], v[176:179], v[84:87]
	v_mfma_f32_16x16x32_bf16 v[80:83], v[200:203], v[176:179], v[80:83]
	v_mfma_f32_16x16x32_bf16 v[68:71], v[192:195], v[184:187], v[68:71]
	v_mfma_f32_16x16x32_bf16 v[64:67], v[200:203], v[184:187], v[64:67]
	v_mfma_f32_16x16x32_bf16 v[116:119], v[196:199], v[160:163], v[116:119]
	v_mfma_f32_16x16x32_bf16 v[112:115], v[204:207], v[160:163], v[112:115]
	v_mfma_f32_16x16x32_bf16 v[100:103], v[196:199], v[168:171], v[100:103]
	v_mfma_f32_16x16x32_bf16 v[96:99], v[204:207], v[168:171], v[96:99]
	v_mfma_f32_16x16x32_bf16 v[84:87], v[196:199], v[180:183], v[84:87]
	v_mfma_f32_16x16x32_bf16 v[80:83], v[204:207], v[180:183], v[80:83]
	v_mfma_f32_16x16x32_bf16 v[68:71], v[196:199], v[188:191], v[68:71]
	v_mfma_f32_16x16x32_bf16 v[64:67], v[204:207], v[188:191], v[64:67]
	s_setprio 0
	s_mov_b32 m0, s60
	s_barrier
; #define PG8_STAGE(bufoff, gbase, voff) do { _Pragma("unroll") for (int _i = 0; _i < 2; ++_i) \
;         __builtin_amdgcn_global_load_lds((const unsigned*)((const char*)(gbase) + (voff)[_i]), (LAS unsigned*)(lds + (bufoff) + ldsw + _i * 8192), 16, 0, 0); } while (0)
; #define PG8_LDA(dst, b, h) do { _Pragma("unroll") for (int m = 0; m < 4; ++m) _Pragma("unroll") for (int k = 0; k < 2; ++k) dst[m][k] = *(const LAS bf16x8*)(lds + PG8_SA(b, h) + aoff + m * 2048 + k * 1024); } while (0)
; #define PG8_LDB(dst, b, h) do { _Pragma("unroll") for (int n = 0; n < 2; ++n) _Pragma("unroll") for (int k = 0; k < 2; ++k) dst[n][k] = *(const LAS bf16x8*)(lds + PG8_SB(b, h) + boff + n * 2048 + k * 1024); } while (0)
; #define PG8_MMA(ai, bj, At, Bt) do { __builtin_amdgcn_s_setprio(1); _Pragma("unroll") for (int m = 0; m < 4; ++m) _Pragma("unroll") for (int n = 0; n < 2; ++n) _Pragma("unroll") for (int k = 0; k < 2; ++k) \
;         acc[ai][bj][m][n] = __builtin_amdgcn_mfma_f32_16x16x32_bf16(Bt[n][k], At[m][k], acc[ai][bj][m][n], 0, 0, 0); __builtin_amdgcn_s_setprio(0); } while (0)
; #define PG8_WAIT_V(n) asm volatile("s_waitcnt vmcnt(" #n ")" ::: "memory")
; #define PG8_WAIT_L(n) asm volatile("s_waitcnt lgkmcnt(" #n ")" ::: "memory")
; #define PG8_BAR __builtin_amdgcn_s_barrier()
; #define PG8_SCHED __builtin_amdgcn_sched_barrier(0)
; template <class Epi>
; __device__ __forceinline__ void gemm_phase(LAS unsigned char* lds, const Gemm g, const StaticOrder& S, const Epi& E, int wv) {
;     ...
;             const bool last = (t == nt - 2);
;             const char* a1 = cA + (ptrdiff_t)(t + 1) * kstep;
;             const char* a2 = last ? nA : cA + (ptrdiff_t)(t + 2) * kstep; const char* b2 = last ? nB : cB + (ptrdiff_t)(t + 2) * kstep;
;             const char* a3 = a2 + kstep; const char* b3 = b2 + kstep;
;             PG8_LDB(B0, 0, 0); PG8_SCHED; PG8_LDA(At, 0, 0); PG8_STAGE(PG8_SA(1, 1), a1 + hstepA, voffA);
;     ...
;             PG8_LDB(B1, 1, 1); PG8_STAGE(PG8_SB(1, 0), b3, voffB);
;             PG8_BAR; PG8_WAIT_L(0); PG8_MMA(0, 1, At, B1); PG8_BAR;
;             PG8_LDA(At, 1, 1); PG8_STAGE(PG8_SA(1, 0), a3, voffA);
;             PG8_BAR; PG8_WAIT_L(0); PG8_MMA(1, 0, At, B0); PG8_BAR; PG8_SCHED;
;             PG8_STAGE(PG8_SB(1, 1), b3 + hstepB, voffB);
;             PG8_WAIT_V(6); PG8_BAR; PG8_MMA(1, 1, At, B1); PG8_BAR;
	ds_read_b128 v[156:159], v175 offset:49152
	ds_read_b128 v[160:163], v175 offset:50176
	ds_read_b128 v[164:167], v175 offset:51200
	ds_read_b128 v[168:171], v175 offset:52224
	ds_read_b128 v[176:179], v175 offset:53248
	ds_read_b128 v[180:183], v175 offset:54272
	ds_read_b128 v[184:187], v175 offset:55296
	ds_read_b128 v[188:191], v175 offset:56320
	global_load_lds_dwordx4 v144, s[100:101]
	s_mov_b32 m0, s61
	s_nop 0
	global_load_lds_dwordx4 v148, s[100:101]
	s_waitcnt vmcnt(10)
	s_barrier
	s_waitcnt lgkmcnt(0)
	s_setprio 1
	s_waitcnt lgkmcnt(0)
	v_mfma_f32_16x16x32_bf16 v[60:63], v[128:131], v[156:159], v[60:63]
	v_mfma_f32_16x16x32_bf16 v[56:59], v[136:139], v[156:159], v[56:59]
	v_mfma_f32_16x16x32_bf16 v[44:47], v[128:131], v[164:167], v[44:47]
	v_mfma_f32_16x16x32_bf16 v[40:43], v[136:139], v[164:167], v[40:43]
	v_mfma_f32_16x16x32_bf16 v[28:31], v[128:131], v[176:179], v[28:31]
	v_mfma_f32_16x16x32_bf16 v[24:27], v[136:139], v[176:179], v[24:27]
	v_mfma_f32_16x16x32_bf16 v[12:15], v[128:131], v[184:187], v[12:15]
	v_mfma_f32_16x16x32_bf16 v[8:11], v[136:139], v[184:187], v[8:11]
	v_mfma_f32_16x16x32_bf16 v[60:63], v[132:135], v[160:163], v[60:63]
	v_mfma_f32_16x16x32_bf16 v[56:59], v[140:143], v[160:163], v[56:59]
	v_mfma_f32_16x16x32_bf16 v[44:47], v[132:135], v[168:171], v[44:47]
	v_mfma_f32_16x16x32_bf16 v[40:43], v[140:143], v[168:171], v[40:43]
	v_mfma_f32_16x16x32_bf16 v[28:31], v[132:135], v[180:183], v[28:31]
	v_mfma_f32_16x16x32_bf16 v[24:27], v[140:143], v[180:183], v[24:27]
	v_mfma_f32_16x16x32_bf16 v[12:15], v[132:135], v[188:191], v[12:15]
	v_mfma_f32_16x16x32_bf16 v[8:11], v[140:143], v[188:191], v[8:11]
	s_setprio 0
	s_barrier
	s_add_u32 s56, s56, 0x1fff80
	s_addc_u32 s57, s57, 0
	s_add_i32 s10, s55, s23
	s_mov_b32 m0, s10
	s_nop 0
	global_load_lds_dwordx4 v146, s[56:57]
	s_add_i32 m0, s10, 0x2000
	s_nop 0
	global_load_lds_dwordx4 v150, s[56:57]
	v_add_u32_e32 v140, s64, v173
	ds_read_b128 v[128:131], v140
	ds_read_b128 v[132:135], v140 offset:1024
	ds_read_b128 v[136:139], v140 offset:2048
	ds_read_b128 v[140:143], v140 offset:3072
	s_waitcnt vmcnt(6)
	s_barrier
	s_setprio 1
	v_mfma_f32_16x16x32_bf16 v[52:55], v[192:195], v[156:159], v[52:55]
	v_mfma_f32_16x16x32_bf16 v[48:51], v[200:203], v[156:159], v[48:51]
	v_mfma_f32_16x16x32_bf16 v[36:39], v[192:195], v[164:167], v[36:39]
	v_mfma_f32_16x16x32_bf16 v[32:35], v[200:203], v[164:167], v[32:35]
	v_mfma_f32_16x16x32_bf16 v[20:23], v[192:195], v[176:179], v[20:23]
	v_mfma_f32_16x16x32_bf16 v[16:19], v[200:203], v[176:179], v[16:19]
	v_mfma_f32_16x16x32_bf16 v[4:7], v[192:195], v[184:187], v[4:7]
	v_mfma_f32_16x16x32_bf16 v[0:3], v[200:203], v[184:187], v[0:3]
	v_mfma_f32_16x16x32_bf16 v[52:55], v[196:199], v[160:163], v[52:55]
	v_mfma_f32_16x16x32_bf16 v[48:51], v[204:207], v[160:163], v[48:51]
	v_mfma_f32_16x16x32_bf16 v[36:39], v[196:199], v[168:171], v[36:39]
	v_mfma_f32_16x16x32_bf16 v[32:35], v[204:207], v[168:171], v[32:35]
	v_mfma_f32_16x16x32_bf16 v[20:23], v[196:199], v[180:183], v[20:23]
	v_mfma_f32_16x16x32_bf16 v[16:19], v[204:207], v[180:183], v[16:19]
	v_mfma_f32_16x16x32_bf16 v[4:7], v[196:199], v[188:191], v[4:7]
	v_mfma_f32_16x16x32_bf16 v[0:3], v[204:207], v[188:191], v[0:3]
	s_setprio 0
	s_waitcnt lgkmcnt(0)
	s_cmpk_gt_u32 s43, 0x7d
	s_mov_b32 s43, s54
	s_barrier
	s_cbranch_scc1 .LBB0_1748
.LBB0_1744:
	ds_read_b128 v[156:159], v175
	ds_read_b128 v[160:163], v175 offset:1024
	ds_read_b128 v[164:167], v175 offset:2048
	ds_read_b128 v[168:171], v175 offset:3072
	ds_read_b128 v[176:179], v175 offset:4096
	ds_read_b128 v[180:183], v175 offset:5120
	ds_read_b128 v[184:187], v175 offset:6144
	ds_read_b128 v[188:191], v175 offset:7168
	s_cmpk_lg_i32 s43, 0x7e
	s_movk_i32 s54, 0x80
	s_cselect_b64 s[56:57], -1, 0
	s_cmpk_eq_i32 s43, 0x7e
	s_mov_b64 s[58:59], s[50:51]
	s_cbranch_scc1 .LBB0_1746
	s_add_i32 s10, s43, 2
	s_lshl_b64 s[54:55], s[10:11], 7
	s_sub_u32 s54, 0, s54
	s_subb_u32 s55, 0, s55
	s_add_u32 s58, s48, s54
	s_addc_u32 s59, s49, s55
	s_mov_b32 s54, s10
